# v25 + R1 cumulative-decay prefix: 32 LDS reads batched, 64 sequential adds, 32 writes (same association)
# baseline (speedup 1.0000x reference)
; #define GAS __attribute__((address_space(1)))
; DI unsigned char* lw(unsigned char* p) { unsigned long long w = (unsigned long long)p; asm volatile("" : "+s"(w)); return (unsigned char*)w; }
; DI void u_rwkv_r1(Frame& F, int c, int h) {
;     ...
;     float lw[8];
;     { const f32x4 x0 = *(const GAS f32x4*)((const float*)(ws + WS_DEC) + go), x1 = *(const GAS f32x4*)((const float*)(ws + WS_DEC) + go + 4);
; #pragma unroll
;       for (int i = 0; i < 4; ++i) { lw[i] = x0[i]; lw[4 + i] = x1[i]; }
; #pragma unroll
;       for (int i = 0; i < 8; ++i) CUM[t * 68 + j0 + i] = lw[i]; }
;     __syncthreads();
;     if (tid < 64) { float s = 0.f;
.LBB0_1073:
	s_lshl_b32 s9, s8, 3
	v_mov_b32_e32 v39, v38
	s_and_b32 s18, s9, 0xffffffc0
	s_ashr_i32 s19, s18, 31
	s_lshl_b32 s9, s8, 6
	v_ashrrev_i32_e32 v36, 3, v39
	s_lshl_b64 s[18:19], s[18:19], 9
	s_and_b32 s9, s9, 0x1c0
	v_ashrrev_i32_e32 v37, 31, v36
	s_or_b32 s18, s18, s9
	v_lshlrev_b32_e32 v12, 3, v39
	v_lshlrev_b64 v[2:3], 9, v[36:37]
	v_and_b32_e32 v18, 56, v12
	v_lshl_add_u64 v[10:11], s[18:19], 0, v[2:3]
	v_or_b32_e32 v10, v10, v18
	v_lshl_add_u64 v[2:3], v[10:11], 2, s[16:17]
	global_load_dwordx4 v[6:9], v[2:3], off
	s_nop 0
	global_load_dwordx4 v[2:5], v[2:3], off offset:16
	v_mul_lo_u32 v13, v36, s94
	v_lshlrev_b32_e32 v14, 2, v18
	v_add3_u32 v13, s20, v13, v14
	v_cmp_gt_i32_e32 vcc, 64, v39
	s_waitcnt vmcnt(0)
	ds_write2_b32 v13, v6, v7 offset1:1
	ds_write2_b32 v13, v8, v9 offset0:2 offset1:3
	ds_write2_b32 v13, v2, v3 offset0:4 offset1:5
	ds_write2_b32 v13, v4, v5 offset0:6 offset1:7
	s_waitcnt lgkmcnt(0)
	s_barrier
	s_and_saveexec_b64 s[18:19], vcc
	s_cbranch_execz .LBB0_1076
; DI void u_rwkv_r1(Frame& F, int c, int h) {
;     ...
;     if (tid < 64) { float s = 0.f;
; #pragma unroll 8
;         for (int tt = 0; tt < 64; ++tt) { s += CUM[tt * 68 + tid]; CUM[tt * 68 + tid] = s; } }
	v_lshl_add_u32 v14, v39, 2, s20
	v_mov_b32_e32 v129, v14
	ds_read2_b32 v[130:131], v129 offset1:68
	ds_read2_b32 v[132:133], v129 offset0:136 offset1:204
	v_add_u32_e32 v129, 0x440, v14
	ds_read2_b32 v[134:135], v129 offset1:68
	ds_read2_b32 v[136:137], v129 offset0:136 offset1:204
	v_add_u32_e32 v129, 0x880, v14
	ds_read2_b32 v[138:139], v129 offset1:68
	ds_read2_b32 v[140:141], v129 offset0:136 offset1:204
	v_add_u32_e32 v129, 0xcc0, v14
	ds_read2_b32 v[142:143], v129 offset1:68
	ds_read2_b32 v[144:145], v129 offset0:136 offset1:204
	v_add_u32_e32 v129, 0x1100, v14
	ds_read2_b32 v[146:147], v129 offset1:68
	ds_read2_b32 v[148:149], v129 offset0:136 offset1:204
	v_add_u32_e32 v129, 0x1540, v14
	ds_read2_b32 v[150:151], v129 offset1:68
	ds_read2_b32 v[152:153], v129 offset0:136 offset1:204
	v_add_u32_e32 v129, 0x1980, v14
	ds_read2_b32 v[154:155], v129 offset1:68
	ds_read2_b32 v[156:157], v129 offset0:136 offset1:204
	v_add_u32_e32 v129, 0x1dc0, v14
	ds_read2_b32 v[158:159], v129 offset1:68
	ds_read2_b32 v[160:161], v129 offset0:136 offset1:204
	v_add_u32_e32 v129, 0x2200, v14
	ds_read2_b32 v[162:163], v129 offset1:68
	ds_read2_b32 v[164:165], v129 offset0:136 offset1:204
	v_add_u32_e32 v129, 0x2640, v14
	ds_read2_b32 v[166:167], v129 offset1:68
	ds_read2_b32 v[168:169], v129 offset0:136 offset1:204
	v_add_u32_e32 v129, 0x2a80, v14
	ds_read2_b32 v[170:171], v129 offset1:68
	ds_read2_b32 v[172:173], v129 offset0:136 offset1:204
	v_add_u32_e32 v129, 0x2ec0, v14
	ds_read2_b32 v[174:175], v129 offset1:68
	ds_read2_b32 v[176:177], v129 offset0:136 offset1:204
	v_add_u32_e32 v129, 0x3300, v14
	ds_read2_b32 v[178:179], v129 offset1:68
	ds_read2_b32 v[180:181], v129 offset0:136 offset1:204
	v_add_u32_e32 v129, 0x3740, v14
	ds_read2_b32 v[182:183], v129 offset1:68
	ds_read2_b32 v[184:185], v129 offset0:136 offset1:204
	v_add_u32_e32 v129, 0x3b80, v14
	ds_read2_b32 v[186:187], v129 offset1:68
	ds_read2_b32 v[188:189], v129 offset0:136 offset1:204
	v_add_u32_e32 v129, 0x3fc0, v14
	ds_read2_b32 v[190:191], v129 offset1:68
	ds_read2_b32 v[192:193], v129 offset0:136 offset1:204
	s_waitcnt lgkmcnt(0)
	v_add_f32_e32 v130, 0, v130
	v_add_f32_e32 v131, v130, v131
	v_add_f32_e32 v132, v131, v132
	v_add_f32_e32 v133, v132, v133
	v_add_f32_e32 v134, v133, v134
	v_add_f32_e32 v135, v134, v135
	v_add_f32_e32 v136, v135, v136
	v_add_f32_e32 v137, v136, v137
	v_add_f32_e32 v138, v137, v138
	v_add_f32_e32 v139, v138, v139
	v_add_f32_e32 v140, v139, v140
	v_add_f32_e32 v141, v140, v141
	v_add_f32_e32 v142, v141, v142
	v_add_f32_e32 v143, v142, v143
	v_add_f32_e32 v144, v143, v144
	v_add_f32_e32 v145, v144, v145
	v_add_f32_e32 v146, v145, v146
	v_add_f32_e32 v147, v146, v147
	v_add_f32_e32 v148, v147, v148
	v_add_f32_e32 v149, v148, v149
	v_add_f32_e32 v150, v149, v150
	v_add_f32_e32 v151, v150, v151
	v_add_f32_e32 v152, v151, v152
	v_add_f32_e32 v153, v152, v153
	v_add_f32_e32 v154, v153, v154
	v_add_f32_e32 v155, v154, v155
	v_add_f32_e32 v156, v155, v156
	v_add_f32_e32 v157, v156, v157
	v_add_f32_e32 v158, v157, v158
	v_add_f32_e32 v159, v158, v159
	v_add_f32_e32 v160, v159, v160
	v_add_f32_e32 v161, v160, v161
	v_add_f32_e32 v162, v161, v162
	v_add_f32_e32 v163, v162, v163
	v_add_f32_e32 v164, v163, v164
	v_add_f32_e32 v165, v164, v165
	v_add_f32_e32 v166, v165, v166
	v_add_f32_e32 v167, v166, v167
	v_add_f32_e32 v168, v167, v168
	v_add_f32_e32 v169, v168, v169
	v_add_f32_e32 v170, v169, v170
	v_add_f32_e32 v171, v170, v171
	v_add_f32_e32 v172, v171, v172
	v_add_f32_e32 v173, v172, v173
	v_add_f32_e32 v174, v173, v174
	v_add_f32_e32 v175, v174, v175
	v_add_f32_e32 v176, v175, v176
	v_add_f32_e32 v177, v176, v177
	v_add_f32_e32 v178, v177, v178
	v_add_f32_e32 v179, v178, v179
	v_add_f32_e32 v180, v179, v180
	v_add_f32_e32 v181, v180, v181
	v_add_f32_e32 v182, v181, v182
	v_add_f32_e32 v183, v182, v183
	v_add_f32_e32 v184, v183, v184
	v_add_f32_e32 v185, v184, v185
	v_add_f32_e32 v186, v185, v186
	v_add_f32_e32 v187, v186, v187
	v_add_f32_e32 v188, v187, v188
	v_add_f32_e32 v189, v188, v189
	v_add_f32_e32 v190, v189, v190
	v_add_f32_e32 v191, v190, v191
	v_add_f32_e32 v192, v191, v192
	v_add_f32_e32 v193, v192, v193
	v_mov_b32_e32 v129, v14
	ds_write2_b32 v129, v130, v131 offset1:68
	ds_write2_b32 v129, v132, v133 offset0:136 offset1:204
	v_add_u32_e32 v129, 0x440, v14
	ds_write2_b32 v129, v134, v135 offset1:68
	ds_write2_b32 v129, v136, v137 offset0:136 offset1:204
	v_add_u32_e32 v129, 0x880, v14
	ds_write2_b32 v129, v138, v139 offset1:68
	ds_write2_b32 v129, v140, v141 offset0:136 offset1:204
	v_add_u32_e32 v129, 0xcc0, v14
	ds_write2_b32 v129, v142, v143 offset1:68
	ds_write2_b32 v129, v144, v145 offset0:136 offset1:204
	v_add_u32_e32 v129, 0x1100, v14
	ds_write2_b32 v129, v146, v147 offset1:68
	ds_write2_b32 v129, v148, v149 offset0:136 offset1:204
	v_add_u32_e32 v129, 0x1540, v14
	ds_write2_b32 v129, v150, v151 offset1:68
	ds_write2_b32 v129, v152, v153 offset0:136 offset1:204
	v_add_u32_e32 v129, 0x1980, v14
	ds_write2_b32 v129, v154, v155 offset1:68
	ds_write2_b32 v129, v156, v157 offset0:136 offset1:204
	v_add_u32_e32 v129, 0x1dc0, v14
	ds_write2_b32 v129, v158, v159 offset1:68
	ds_write2_b32 v129, v160, v161 offset0:136 offset1:204
	v_add_u32_e32 v129, 0x2200, v14
	ds_write2_b32 v129, v162, v163 offset1:68
	ds_write2_b32 v129, v164, v165 offset0:136 offset1:204
	v_add_u32_e32 v129, 0x2640, v14
	ds_write2_b32 v129, v166, v167 offset1:68
	ds_write2_b32 v129, v168, v169 offset0:136 offset1:204
	v_add_u32_e32 v129, 0x2a80, v14
	ds_write2_b32 v129, v170, v171 offset1:68
	ds_write2_b32 v129, v172, v173 offset0:136 offset1:204
	v_add_u32_e32 v129, 0x2ec0, v14
	ds_write2_b32 v129, v174, v175 offset1:68
	ds_write2_b32 v129, v176, v177 offset0:136 offset1:204
	v_add_u32_e32 v129, 0x3300, v14
	ds_write2_b32 v129, v178, v179 offset1:68
	ds_write2_b32 v129, v180, v181 offset0:136 offset1:204
	v_add_u32_e32 v129, 0x3740, v14
	ds_write2_b32 v129, v182, v183 offset1:68
	ds_write2_b32 v129, v184, v185 offset0:136 offset1:204
	v_add_u32_e32 v129, 0x3b80, v14
	ds_write2_b32 v129, v186, v187 offset1:68
	ds_write2_b32 v129, v188, v189 offset0:136 offset1:204
	v_add_u32_e32 v129, 0x3fc0, v14
	ds_write2_b32 v129, v190, v191 offset1:68
	ds_write2_b32 v129, v192, v193 offset0:136 offset1:204
	s_movk_i32 s9, 0x4400

; #define GAS __attribute__((address_space(1)))
; DI unsigned char* lw(unsigned char* p) { unsigned long long w = (unsigned long long)p; asm volatile("" : "+s"(w)); return (unsigned char*)w; }
; DI void u_rwkv_r1(Frame& F, int c, int h) {
;     ...
;     float lw[8];
;     { const f32x4 x0 = *(const GAS f32x4*)((const float*)(ws + WS_DEC) + go), x1 = *(const GAS f32x4*)((const float*)(ws + WS_DEC) + go + 4);
; #pragma unroll
;       for (int i = 0; i < 4; ++i) { lw[i] = x0[i]; lw[4 + i] = x1[i]; }
; #pragma unroll
;       for (int i = 0; i < 8; ++i) CUM[t * 68 + j0 + i] = lw[i]; }
;     __syncthreads();
;     if (tid < 64) { float s = 0.f;
.LBB0_1629:
	s_lshl_b32 s3, s2, 3
	v_mov_b32_e32 v39, v38
	s_and_b32 s18, s3, 0xffffffc0
	s_ashr_i32 s19, s18, 31
	s_lshl_b32 s3, s2, 6
	v_ashrrev_i32_e32 v36, 3, v39
	s_lshl_b64 s[18:19], s[18:19], 9
	s_and_b32 s3, s3, 0x1c0
	v_ashrrev_i32_e32 v37, 31, v36
	s_or_b32 s18, s18, s3
	v_lshlrev_b32_e32 v12, 3, v39
	v_lshlrev_b64 v[2:3], 9, v[36:37]
	v_and_b32_e32 v18, 56, v12
	v_lshl_add_u64 v[10:11], s[18:19], 0, v[2:3]
	v_or_b32_e32 v10, v10, v18
	v_lshl_add_u64 v[2:3], v[10:11], 2, s[8:9]
	global_load_dwordx4 v[6:9], v[2:3], off
	s_nop 0
	global_load_dwordx4 v[2:5], v[2:3], off offset:16
	v_mul_lo_u32 v13, v36, s94
	v_lshlrev_b32_e32 v14, 2, v18
	v_add3_u32 v13, s11, v13, v14
	v_cmp_gt_i32_e32 vcc, 64, v39
	s_waitcnt vmcnt(0)
	ds_write2_b32 v13, v6, v7 offset1:1
	ds_write2_b32 v13, v8, v9 offset0:2 offset1:3
	ds_write2_b32 v13, v2, v3 offset0:4 offset1:5
	ds_write2_b32 v13, v4, v5 offset0:6 offset1:7
	s_waitcnt lgkmcnt(0)
	s_barrier
	s_and_saveexec_b64 s[18:19], vcc
	s_cbranch_execz .LBB0_1632
; DI void u_rwkv_r1(Frame& F, int c, int h) {
;     ...
;     if (tid < 64) { float s = 0.f;
; #pragma unroll 8
;         for (int tt = 0; tt < 64; ++tt) { s += CUM[tt * 68 + tid]; CUM[tt * 68 + tid] = s; } }
	v_lshl_add_u32 v14, v39, 2, s11
	v_mov_b32_e32 v129, v14
	ds_read2_b32 v[130:131], v129 offset1:68
	ds_read2_b32 v[132:133], v129 offset0:136 offset1:204
	v_add_u32_e32 v129, 0x440, v14
	ds_read2_b32 v[134:135], v129 offset1:68
	ds_read2_b32 v[136:137], v129 offset0:136 offset1:204
	v_add_u32_e32 v129, 0x880, v14
	ds_read2_b32 v[138:139], v129 offset1:68
	ds_read2_b32 v[140:141], v129 offset0:136 offset1:204
	v_add_u32_e32 v129, 0xcc0, v14
	ds_read2_b32 v[142:143], v129 offset1:68
	ds_read2_b32 v[144:145], v129 offset0:136 offset1:204
	v_add_u32_e32 v129, 0x1100, v14
	ds_read2_b32 v[146:147], v129 offset1:68
	ds_read2_b32 v[148:149], v129 offset0:136 offset1:204
	v_add_u32_e32 v129, 0x1540, v14
	ds_read2_b32 v[150:151], v129 offset1:68
	ds_read2_b32 v[152:153], v129 offset0:136 offset1:204
	v_add_u32_e32 v129, 0x1980, v14
	ds_read2_b32 v[154:155], v129 offset1:68
	ds_read2_b32 v[156:157], v129 offset0:136 offset1:204
	v_add_u32_e32 v129, 0x1dc0, v14
	ds_read2_b32 v[158:159], v129 offset1:68
	ds_read2_b32 v[160:161], v129 offset0:136 offset1:204
	v_add_u32_e32 v129, 0x2200, v14
	ds_read2_b32 v[162:163], v129 offset1:68
	ds_read2_b32 v[164:165], v129 offset0:136 offset1:204
	v_add_u32_e32 v129, 0x2640, v14
	ds_read2_b32 v[166:167], v129 offset1:68
	ds_read2_b32 v[168:169], v129 offset0:136 offset1:204
	v_add_u32_e32 v129, 0x2a80, v14
	ds_read2_b32 v[170:171], v129 offset1:68
	ds_read2_b32 v[172:173], v129 offset0:136 offset1:204
	v_add_u32_e32 v129, 0x2ec0, v14
	ds_read2_b32 v[174:175], v129 offset1:68
	ds_read2_b32 v[176:177], v129 offset0:136 offset1:204
	v_add_u32_e32 v129, 0x3300, v14
	ds_read2_b32 v[178:179], v129 offset1:68
	ds_read2_b32 v[180:181], v129 offset0:136 offset1:204
	v_add_u32_e32 v129, 0x3740, v14
	ds_read2_b32 v[182:183], v129 offset1:68
	ds_read2_b32 v[184:185], v129 offset0:136 offset1:204
	v_add_u32_e32 v129, 0x3b80, v14
	ds_read2_b32 v[186:187], v129 offset1:68
	ds_read2_b32 v[188:189], v129 offset0:136 offset1:204
	v_add_u32_e32 v129, 0x3fc0, v14
	ds_read2_b32 v[190:191], v129 offset1:68
	ds_read2_b32 v[192:193], v129 offset0:136 offset1:204
	s_waitcnt lgkmcnt(0)
	v_add_f32_e32 v130, 0, v130
	v_add_f32_e32 v131, v130, v131
	v_add_f32_e32 v132, v131, v132
	v_add_f32_e32 v133, v132, v133
	v_add_f32_e32 v134, v133, v134
	v_add_f32_e32 v135, v134, v135
	v_add_f32_e32 v136, v135, v136
	v_add_f32_e32 v137, v136, v137
	v_add_f32_e32 v138, v137, v138
	v_add_f32_e32 v139, v138, v139
	v_add_f32_e32 v140, v139, v140
	v_add_f32_e32 v141, v140, v141
	v_add_f32_e32 v142, v141, v142
	v_add_f32_e32 v143, v142, v143
	v_add_f32_e32 v144, v143, v144
	v_add_f32_e32 v145, v144, v145
	v_add_f32_e32 v146, v145, v146
	v_add_f32_e32 v147, v146, v147
	v_add_f32_e32 v148, v147, v148
	v_add_f32_e32 v149, v148, v149
	v_add_f32_e32 v150, v149, v150
	v_add_f32_e32 v151, v150, v151
	v_add_f32_e32 v152, v151, v152
	v_add_f32_e32 v153, v152, v153
	v_add_f32_e32 v154, v153, v154
	v_add_f32_e32 v155, v154, v155
	v_add_f32_e32 v156, v155, v156
	v_add_f32_e32 v157, v156, v157
	v_add_f32_e32 v158, v157, v158
	v_add_f32_e32 v159, v158, v159
	v_add_f32_e32 v160, v159, v160
	v_add_f32_e32 v161, v160, v161
	v_add_f32_e32 v162, v161, v162
	v_add_f32_e32 v163, v162, v163
	v_add_f32_e32 v164, v163, v164
	v_add_f32_e32 v165, v164, v165
	v_add_f32_e32 v166, v165, v166
	v_add_f32_e32 v167, v166, v167
	v_add_f32_e32 v168, v167, v168
	v_add_f32_e32 v169, v168, v169
	v_add_f32_e32 v170, v169, v170
	v_add_f32_e32 v171, v170, v171
	v_add_f32_e32 v172, v171, v172
	v_add_f32_e32 v173, v172, v173
	v_add_f32_e32 v174, v173, v174
	v_add_f32_e32 v175, v174, v175
	v_add_f32_e32 v176, v175, v176
	v_add_f32_e32 v177, v176, v177
	v_add_f32_e32 v178, v177, v178
	v_add_f32_e32 v179, v178, v179
	v_add_f32_e32 v180, v179, v180
	v_add_f32_e32 v181, v180, v181
	v_add_f32_e32 v182, v181, v182
	v_add_f32_e32 v183, v182, v183
	v_add_f32_e32 v184, v183, v184
	v_add_f32_e32 v185, v184, v185
	v_add_f32_e32 v186, v185, v186
	v_add_f32_e32 v187, v186, v187
	v_add_f32_e32 v188, v187, v188
	v_add_f32_e32 v189, v188, v189
	v_add_f32_e32 v190, v189, v190
	v_add_f32_e32 v191, v190, v191
	v_add_f32_e32 v192, v191, v192
	v_add_f32_e32 v193, v192, v193
	v_mov_b32_e32 v129, v14
	ds_write2_b32 v129, v130, v131 offset1:68
	ds_write2_b32 v129, v132, v133 offset0:136 offset1:204
	v_add_u32_e32 v129, 0x440, v14
	ds_write2_b32 v129, v134, v135 offset1:68
	ds_write2_b32 v129, v136, v137 offset0:136 offset1:204
	v_add_u32_e32 v129, 0x880, v14
	ds_write2_b32 v129, v138, v139 offset1:68
	ds_write2_b32 v129, v140, v141 offset0:136 offset1:204
	v_add_u32_e32 v129, 0xcc0, v14
	ds_write2_b32 v129, v142, v143 offset1:68
	ds_write2_b32 v129, v144, v145 offset0:136 offset1:204
	v_add_u32_e32 v129, 0x1100, v14
	ds_write2_b32 v129, v146, v147 offset1:68
	ds_write2_b32 v129, v148, v149 offset0:136 offset1:204
	v_add_u32_e32 v129, 0x1540, v14
	ds_write2_b32 v129, v150, v151 offset1:68
	ds_write2_b32 v129, v152, v153 offset0:136 offset1:204
	v_add_u32_e32 v129, 0x1980, v14
	ds_write2_b32 v129, v154, v155 offset1:68
	ds_write2_b32 v129, v156, v157 offset0:136 offset1:204
	v_add_u32_e32 v129, 0x1dc0, v14
	ds_write2_b32 v129, v158, v159 offset1:68
	ds_write2_b32 v129, v160, v161 offset0:136 offset1:204
	v_add_u32_e32 v129, 0x2200, v14
	ds_write2_b32 v129, v162, v163 offset1:68
	ds_write2_b32 v129, v164, v165 offset0:136 offset1:204
	v_add_u32_e32 v129, 0x2640, v14
	ds_write2_b32 v129, v166, v167 offset1:68
	ds_write2_b32 v129, v168, v169 offset0:136 offset1:204
	v_add_u32_e32 v129, 0x2a80, v14
	ds_write2_b32 v129, v170, v171 offset1:68
	ds_write2_b32 v129, v172, v173 offset0:136 offset1:204
	v_add_u32_e32 v129, 0x2ec0, v14
	ds_write2_b32 v129, v174, v175 offset1:68
	ds_write2_b32 v129, v176, v177 offset0:136 offset1:204
	v_add_u32_e32 v129, 0x3300, v14
	ds_write2_b32 v129, v178, v179 offset1:68
	ds_write2_b32 v129, v180, v181 offset0:136 offset1:204
	v_add_u32_e32 v129, 0x3740, v14
	ds_write2_b32 v129, v182, v183 offset1:68
	ds_write2_b32 v129, v184, v185 offset0:136 offset1:204
	v_add_u32_e32 v129, 0x3b80, v14
	ds_write2_b32 v129, v186, v187 offset1:68
	ds_write2_b32 v129, v188, v189 offset0:136 offset1:204
	v_add_u32_e32 v129, 0x3fc0, v14
	ds_write2_b32 v129, v190, v191 offset1:68
	ds_write2_b32 v129, v192, v193 offset0:136 offset1:204
	s_movk_i32 s3, 0x4400
